# overlap v12: all 256 workgroups run the first two GEMM rounds, 32 per-row-tile counters, look-ahead polling without invalidate in the recurrence
# speedup vs baseline: 1.0056x; 1.0056x over previous
.LBB0_124:
	s_mov_b32 s98, 0
	s_mov_b32 s4, s3
	s_cmpk_lt_u32 s4, 0x1000
	s_cbranch_scc0 .Lmap_smp_first
	s_lshr_b32 s5, s4, 7
	s_and_b32 s9, s4, 7
	s_lshl_b32 s9, s9, 5
	s_add_u32 s8, s9, s5
	s_bfe_u32 s81, s4, 0x40003
	s_branch .Lmap_done_first

.LBB0_131:
.Lsig_check:
	s_cmp_gt_u32 s98, 31
	s_cbranch_scc1 .Lsig_end
	s_cmp_lt_u32 s98, 4
	s_cbranch_scc1 .Lsig_small
	s_cmpk_lt_u32 s3, 64
	s_cbranch_scc1 .Lsig_end
	s_lshl_b32 s99, s98, 7
	s_sub_u32 s99, s99, 0x181
	s_mul_i32 s99, s99, 0xaaab
	s_lshr_b32 s99, s99, 23
	s_add_u32 s99, s99, 4
	s_branch .Lsig_thr
.Lsig_small:
	s_lshr_b32 s99, s98, 1
	s_add_u32 s99, s99, 2
.Lsig_thr:
	s_cmp_lg_u64 s[4:5], 0
	s_cbranch_scc1 .Lsig_last
	s_cmp_ge_u32 s35, s99
	s_cbranch_scc0 .Lsig_end
	s_waitcnt vmcnt(24)
	s_branch .Lsig_go

.Lsig_go:
	s_barrier
	v_readfirstlane_b32 s99, v208
	s_lshr_b32 s99, s99, 6
	s_cmp_lg_u32 s99, 4
	s_cbranch_scc1 .Lsig_skipw
	s_lshl_b32 s99, s98, 4
	s_add_u32 s99, s99, 0x3800
	v_mov_b32_e32 v253, s99
	v_mov_b32_e32 v254, 1
	s_mov_b64 s[100:101], exec
	s_mov_b64 exec, 1
	global_atomic_add v253, v254, s[74:75]
	s_mov_b64 exec, s[100:101]

.LBB0_134:
	s_cmp_lt_u32 s35, 2
	s_cbranch_scc0 .Lnx_late
	s_lshl_b32 s4, s35, 8
	s_add_u32 s4, s4, s3
	s_branch .Lnx_map
.Lnx_late:
	s_cmpk_lt_u32 s3, 64
	s_cbranch_scc0 .Lnx_p1
	s_movk_i32 s4, 0x7fff
	s_branch .Lnx_map
.Lnx_p1:
	s_sub_u32 s4, s35, 2
	s_mul_i32 s4, s4, 0xc0
	s_add_u32 s4, s4, s3
	s_add_u32 s4, s4, 0x1c0
.Lnx_map:
	s_cmpk_lt_u32 s4, 0x1000
	s_cbranch_scc0 .Lmap_smp_next
	s_lshr_b32 s5, s4, 7
	s_and_b32 s9, s4, 7
	s_lshl_b32 s9, s9, 5
	s_add_u32 s20, s9, s5
	s_bfe_u32 s80, s4, 0x40003
	s_branch .Lmap_done_next

.Lovl_after_p1:
	s_cmpk_lt_u32 s3, 64
	s_cbranch_scc1 .Lovl_p2_entry
	s_waitcnt vmcnt(0)
	v_mov_b32_e32 v253, 0x3a00
	v_readfirstlane_b32 s99, v208
	s_lshr_b32 s99, s99, 6
	s_cmp_lg_u32 s99, 0
	s_cbranch_scc1 .Lovl_c4_nosig
	buffer_wbl2 sc1
	s_waitcnt vmcnt(0)
	v_mov_b32_e32 v254, 1
	s_mov_b64 s[100:101], exec
	s_mov_b64 exec, 1
	global_atomic_add v253, v254, s[74:75]
	s_mov_b64 exec, s[100:101]

.LBB0_469:
	s_and_b64 vcc, exec, s[0:1]
	s_cbranch_vccz .LBB0_354
	v_mov_b32_e32 v253, 0x3800
	s_movk_i32 s101, 0x100
	v_readfirstlane_b32 s99, v208
	s_lshr_b32 s99, s99, 6
	s_cmp_lg_u32 s99, 0
	s_cbranch_scc1 .Lhs_join_g0
	s_mov_b32 s99, 0

.Lhs_chk_g0:
	s_waitcnt vmcnt(0)
	v_readfirstlane_b32 s100, v254
	s_cmp_ge_u32 s100, s101
	s_cbranch_scc1 .Lhs_join_g0
	s_sleep 4
	s_add_u32 s99, s99, 1
	s_cmp_lt_u32 s99, 0x8000
	s_cbranch_scc1 .Lhs_g0

.LBB0_472:
	s_and_b32 s98, s71, 3
	s_cmp_gt_u32 s98, 1
	s_cbranch_scc1 .Lhw_skip
	s_cmp_lt_u32 s71, 2
	s_cbranch_scc1 .Lhw_skip
	s_lshr_b32 s99, s71, 2
	s_sub_u32 s99, 32, s99
	s_movk_i32 s100, 0x100
	s_cmp_lt_u32 s99, 4
	s_cselect_b32 s101, s100, 0xc0
	s_lshl_b32 s99, s99, 4
	s_add_u32 s99, s99, 0x3800
	v_mov_b32_e32 v253, s99
	s_cmp_eq_u32 s98, 0
	s_cbranch_scc1 .Lhw_wait
	v_readfirstlane_b32 s99, v208
	s_lshr_b32 s99, s99, 6
	s_cmp_lg_u32 s99, 0
	s_cbranch_scc1 .Lhw_skip
	global_load_dword v254, v253, s[74:75] sc1
	s_branch .Lhw_skip
